# P4 LoRA GEMM: epilogue w0/a0 vector loads issued in the k-iteration's phase 1 (counted waits 12), epilogue has no vmcnt waits so the next tile's DMA stays in flight through it
# speedup vs baseline: 1.0017x; 1.0017x over previous
; #define PG8_STAGE(bufoff, gbase, voff) do { _Pragma("unroll") for (int _i = 0; _i < 2; ++_i) \
;         __builtin_amdgcn_global_load_lds((const unsigned*)((const char*)(gbase) + (voff)[_i]), (PG8_LAS unsigned*)(lds + (bufoff) + ldsw + _i * 8192), 16, 0, 0); } while (0)
; #define PG8_LDA(dst, b, h) do { _Pragma("unroll") for (int m = 0; m < 4; ++m) _Pragma("unroll") for (int k = 0; k < 2; ++k) dst[m][k] = *(const PG8_LAS bf16x8*)(lds + PG8_SA(b, h) + aoff + m * 2048 + k * 1024); } while (0)
; #define PG8_LDB(dst, b, h) do { _Pragma("unroll") for (int n = 0; n < 2; ++n) _Pragma("unroll") for (int k = 0; k < 2; ++k) dst[n][k] = *(const PG8_LAS bf16x8*)(lds + PG8_SB(b, h) + boff + n * 2048 + k * 1024); } while (0)
; #define PG8_WAIT_V(n) asm volatile("s_waitcnt vmcnt(" #n ")" ::: "memory")
; #define PG8_WAIT_L(n) asm volatile("s_waitcnt lgkmcnt(" #n ")" ::: "memory")
; #define PG8_BAR __builtin_amdgcn_s_barrier()
; #define PG8_SCHED __builtin_amdgcn_sched_barrier(0)
; template <class Epi, class Sched, bool ALIGN_EPI = false, bool SP2 = false>
; __device__ __forceinline__ void gemm_phase(PG8_LAS unsigned char* lds, const Gemm g, const Sched& S, const Epi& E) {
;     ...
;             PG8_LDB(B0, 0, 0); PG8_LDB(B1, 0, 1); PG8_SCHED; PG8_LDA(At, 0, 0); PG8_STAGE(PG8_SA(1, 1), a1 + hstepA, voffA);
;             PG8_WAIT_V(8); PG8_WAIT_L(0); PG8_BAR; PG8_MMA(0, 0, At, B0); PG8_MMA(0, 1, At, B1); PG8_BAR; PG8_SCHED;
;             PG8_LDA(At, 0, 1); PG8_STAGE(PG8_SB(0, 0), b2, voffB); PG8_STAGE(PG8_SB(0, 1), b2 + hstepB, voffB); PG8_STAGE(PG8_SA(0, 0), a2, voffA);
;             PG8_WAIT_V(8); PG8_WAIT_L(0); PG8_BAR; PG8_MMA(1, 0, At, B0); PG8_MMA(1, 1, At, B1); PG8_BAR; PG8_SCHED;
;     __device__ __forceinline__ void operator()(const af4 (&acc)[2][2][4][2], const pg8::Unit& u, int wr, int wc, int fr, int fq) const {
;         const int kind = u.pn >> 3, dir = kind & 1, cb = (u.pn & 7) * 256 + wc * 32 + 8 * fq, row0 = u.pm * 256 + wr * 64 + fr;
;         const float* bias = (kind < 2 ? w0 : a0) + dir * BW;
;         const float sc = kind < 2 ? 0.6065306597126334f * 1.4426950408889634f : 1.0f;
; #pragma unroll
;         for (int bj = 0; bj < 2; ++bj) {
;             const int c = cb + bj * 128;
;             const af4 bb[2] = {*(const GAS af4*)(bias + c) * -1.4426950408889634f, *(const GAS af4*)(bias + c + 4) * -1.4426950408889634f};
.LBB0_524:
	ds_read_b128 v[150:153], v161
	ds_read_b128 v[154:157], v161 offset:1024
	ds_read_b128 v[166:169], v161 offset:2048
	ds_read_b128 v[170:173], v161 offset:3072
	ds_read_b128 v[174:177], v162
	ds_read_b128 v[178:181], v162 offset:1024
	ds_read_b128 v[182:185], v162 offset:2048
	ds_read_b128 v[186:189], v162 offset:3072
	s_add_i32 s75, s24, 2
	s_add_u32 s68, s66, 0x100
	s_addc_u32 s69, s67, 0
	s_cmp_eq_u32 s44, s24
	s_cselect_b32 s24, s6, s68
	s_cselect_b32 s25, s7, s69
	s_cselect_b32 s77, s61, s74
	s_cselect_b32 s76, s60, s73
	v_lshl_add_u64 v[158:159], s[66:67], 0, v[140:141]
	s_add_i32 m0, s36, 0xc000
	ds_read_b128 v[190:193], v163
	ds_read_b128 v[194:197], v163 offset:1024
	ds_read_b128 v[198:201], v163 offset:2048
	ds_read_b128 v[202:205], v163 offset:3072
	ds_read_b128 v[206:209], v163 offset:4096
	ds_read_b128 v[210:213], v163 offset:5120
	ds_read_b128 v[214:217], v163 offset:6144
	ds_read_b128 v[218:221], v163 offset:7168
	global_load_lds_dwordx4 v[158:159], off
	v_lshl_add_u64 v[158:159], s[66:67], 0, v[142:143]
	s_add_i32 m0, s36, 0xe000
	s_nop 0
	global_load_lds_dwordx4 v[158:159], off
	s_ashr_i32 s98, s49, 3
	s_cmp_lt_i32 s98, 2
	s_cselect_b32 s99, 26, 30
	s_lshl_b32 s98, s98, 13
	s_and_b32 s98, s98, 0x2000
	s_nop 0
	v_readlane_b32 s100, v254, s99
	s_add_i32 s99, s99, 1
	s_nop 1
	v_readlane_b32 s101, v254, s99
	s_lshl_b32 s99, s49, 8
	s_and_b32 s99, s99, 0x700
	v_or_b32_e32 v250, s99, v160
	v_lshlrev_b32_e32 v250, 2, v250
	s_add_u32 s100, s100, s98
	s_addc_u32 s101, s101, 0
	s_nop 0
	global_load_dwordx4 v[234:237], v250, s[100:101] offset:16
	global_load_dwordx4 v[238:241], v250, s[100:101]
	global_load_dwordx4 v[242:245], v250, s[100:101] offset:528
	global_load_dwordx4 v[246:249], v250, s[100:101] offset:512
	s_waitcnt vmcnt(12)
	s_waitcnt lgkmcnt(0)
	s_barrier
	s_setprio 1
	s_waitcnt lgkmcnt(0)
	v_mfma_f32_16x16x32_bf16 v[126:129], v[150:153], v[190:193], v[126:129]
	v_mfma_f32_16x16x32_bf16 v[122:125], v[166:169], v[190:193], v[122:125]
	v_mfma_f32_16x16x32_bf16 v[118:121], v[150:153], v[198:201], v[118:121]
	v_mfma_f32_16x16x32_bf16 v[114:117], v[166:169], v[198:201], v[114:117]
	v_mfma_f32_16x16x32_bf16 v[110:113], v[150:153], v[206:209], v[110:113]
	v_mfma_f32_16x16x32_bf16 v[106:109], v[166:169], v[206:209], v[106:109]
	v_mfma_f32_16x16x32_bf16 v[102:105], v[150:153], v[214:217], v[102:105]
	v_mfma_f32_16x16x32_bf16 v[98:101], v[166:169], v[214:217], v[98:101]
	v_mfma_f32_16x16x32_bf16 v[126:129], v[154:157], v[194:197], v[126:129]
	v_mfma_f32_16x16x32_bf16 v[122:125], v[170:173], v[194:197], v[122:125]
	v_mfma_f32_16x16x32_bf16 v[118:121], v[154:157], v[202:205], v[118:121]
	v_mfma_f32_16x16x32_bf16 v[114:117], v[170:173], v[202:205], v[114:117]
	v_mfma_f32_16x16x32_bf16 v[110:113], v[154:157], v[210:213], v[110:113]
	v_mfma_f32_16x16x32_bf16 v[106:109], v[170:173], v[210:213], v[106:109]
	v_mfma_f32_16x16x32_bf16 v[102:105], v[154:157], v[218:221], v[102:105]
	v_mfma_f32_16x16x32_bf16 v[98:101], v[170:173], v[218:221], v[98:101]
	s_setprio 0
	s_setprio 1
	v_mfma_f32_16x16x32_bf16 v[62:65], v[174:177], v[190:193], v[62:65]
	v_mfma_f32_16x16x32_bf16 v[58:61], v[182:185], v[190:193], v[58:61]
	v_mfma_f32_16x16x32_bf16 v[54:57], v[174:177], v[198:201], v[54:57]
	v_mfma_f32_16x16x32_bf16 v[50:53], v[182:185], v[198:201], v[50:53]
	v_mfma_f32_16x16x32_bf16 v[46:49], v[174:177], v[206:209], v[46:49]
	v_mfma_f32_16x16x32_bf16 v[42:45], v[182:185], v[206:209], v[42:45]
	v_mfma_f32_16x16x32_bf16 v[38:41], v[174:177], v[214:217], v[38:41]
	v_mfma_f32_16x16x32_bf16 v[34:37], v[182:185], v[214:217], v[34:37]
	v_mfma_f32_16x16x32_bf16 v[62:65], v[178:181], v[194:197], v[62:65]
	v_mfma_f32_16x16x32_bf16 v[58:61], v[186:189], v[194:197], v[58:61]
	v_mfma_f32_16x16x32_bf16 v[54:57], v[178:181], v[202:205], v[54:57]
	v_mfma_f32_16x16x32_bf16 v[50:53], v[186:189], v[202:205], v[50:53]
	v_mfma_f32_16x16x32_bf16 v[46:49], v[178:181], v[210:213], v[46:49]
	v_mfma_f32_16x16x32_bf16 v[42:45], v[186:189], v[210:213], v[42:45]
	v_mfma_f32_16x16x32_bf16 v[38:41], v[178:181], v[218:221], v[38:41]
	v_mfma_f32_16x16x32_bf16 v[34:37], v[186:189], v[218:221], v[34:37]
	s_setprio 0
	s_barrier
	s_add_i32 s66, s45, s21
	v_lshl_add_u64 v[158:159], s[76:77], 0, v[134:135]
	s_mov_b32 m0, s66
	ds_read_b128 v[190:193], v163 offset:16384
	ds_read_b128 v[194:197], v163 offset:17408
	ds_read_b128 v[198:201], v163 offset:18432
	ds_read_b128 v[202:205], v163 offset:19456
	ds_read_b128 v[206:209], v163 offset:20480
	ds_read_b128 v[210:213], v163 offset:21504
	ds_read_b128 v[214:217], v163 offset:22528
	ds_read_b128 v[218:221], v163 offset:23552
	global_load_lds_dwordx4 v[158:159], off
	s_add_i32 m0, s66, 0x2000
	s_add_u32 s66, s76, s8
	v_lshl_add_u64 v[222:223], s[76:77], 0, v[130:131]
	s_addc_u32 s67, s77, s9
	s_add_i32 s76, s46, s21
	global_load_lds_dwordx4 v[222:223], off
	v_lshl_add_u64 v[224:225], s[66:67], 0, v[134:135]
	s_mov_b32 m0, s76
	v_lshl_add_u64 v[226:227], s[66:67], 0, v[130:131]
	global_load_lds_dwordx4 v[224:225], off
	s_add_i32 m0, s76, 0x2000
	v_lshl_add_u64 v[228:229], s[24:25], 0, v[136:137]
	global_load_lds_dwordx4 v[226:227], off
	s_mov_b32 m0, s36
	v_lshl_add_u64 v[230:231], s[24:25], 0, v[132:133]
	global_load_lds_dwordx4 v[228:229], off
	s_mov_b32 m0, s37
	s_nop 0
	global_load_lds_dwordx4 v[230:231], off
	s_waitcnt vmcnt(12)
	s_waitcnt lgkmcnt(0)
	s_barrier
; #define PG8_STAGE(bufoff, gbase, voff) do { _Pragma("unroll") for (int _i = 0; _i < 2; ++_i) \
;         __builtin_amdgcn_global_load_lds((const unsigned*)((const char*)(gbase) + (voff)[_i]), (PG8_LAS unsigned*)(lds + (bufoff) + ldsw + _i * 8192), 16, 0, 0); } while (0)
; #define PG8_LDA(dst, b, h) do { _Pragma("unroll") for (int m = 0; m < 4; ++m) _Pragma("unroll") for (int k = 0; k < 2; ++k) dst[m][k] = *(const PG8_LAS bf16x8*)(lds + PG8_SA(b, h) + aoff + m * 2048 + k * 1024); } while (0)
; #define PG8_LDB(dst, b, h) do { _Pragma("unroll") for (int n = 0; n < 2; ++n) _Pragma("unroll") for (int k = 0; k < 2; ++k) dst[n][k] = *(const PG8_LAS bf16x8*)(lds + PG8_SB(b, h) + boff + n * 2048 + k * 1024); } while (0)
; #define PG8_MMA(ai, bj, At, Bt) do { __builtin_amdgcn_s_setprio(1); _Pragma("unroll") for (int m = 0; m < 4; ++m) _Pragma("unroll") for (int n = 0; n < 2; ++n) _Pragma("unroll") for (int k = 0; k < 2; ++k) \
;         acc[ai][bj][m][n] = __builtin_amdgcn_mfma_f32_16x16x32_bf16(Bt[n][k], At[m][k], acc[ai][bj][m][n], 0, 0, 0); __builtin_amdgcn_s_setprio(0); } while (0)
; #define PG8_WAIT_V(n) asm volatile("s_waitcnt vmcnt(" #n ")" ::: "memory")
; #define PG8_WAIT_L(n) asm volatile("s_waitcnt lgkmcnt(" #n ")" ::: "memory")
; #define PG8_BAR __builtin_amdgcn_s_barrier()
; #define PG8_SCHED __builtin_amdgcn_sched_barrier(0)
; template <class Epi, class Sched, bool ALIGN_EPI = false, bool SP2 = false>
; __device__ __forceinline__ void gemm_phase(PG8_LAS unsigned char* lds, const Gemm g, const Sched& S, const Epi& E) {
;     ...
;             PG8_WAIT_V(8); PG8_WAIT_L(0); PG8_BAR; PG8_MMA(1, 0, At, B0); PG8_MMA(1, 1, At, B1); PG8_BAR; PG8_SCHED;
;             PG8_LDB(B0, 1, 0); PG8_LDB(B1, 1, 1); PG8_SCHED; PG8_LDA(At, 1, 0); PG8_STAGE(PG8_SA(0, 1), a2 + hstepA, voffA);
;             PG8_WAIT_V(8); PG8_WAIT_L(0); PG8_BAR; PG8_MMA(0, 0, At, B0); PG8_MMA(0, 1, At, B1); PG8_BAR; PG8_SCHED;
	s_setprio 1
	s_waitcnt lgkmcnt(0)
	v_mfma_f32_16x16x32_bf16 v[94:97], v[150:153], v[190:193], v[94:97]
	v_mfma_f32_16x16x32_bf16 v[90:93], v[166:169], v[190:193], v[90:93]
	v_mfma_f32_16x16x32_bf16 v[86:89], v[150:153], v[198:201], v[86:89]
	v_mfma_f32_16x16x32_bf16 v[82:85], v[166:169], v[198:201], v[82:85]
	v_mfma_f32_16x16x32_bf16 v[78:81], v[150:153], v[206:209], v[78:81]
	v_mfma_f32_16x16x32_bf16 v[74:77], v[166:169], v[206:209], v[74:77]
	v_mfma_f32_16x16x32_bf16 v[70:73], v[150:153], v[214:217], v[70:73]
	v_mfma_f32_16x16x32_bf16 v[66:69], v[166:169], v[214:217], v[66:69]
	v_mfma_f32_16x16x32_bf16 v[94:97], v[154:157], v[194:197], v[94:97]
	v_mfma_f32_16x16x32_bf16 v[90:93], v[170:173], v[194:197], v[90:93]
	v_mfma_f32_16x16x32_bf16 v[86:89], v[154:157], v[202:205], v[86:89]
	v_mfma_f32_16x16x32_bf16 v[82:85], v[170:173], v[202:205], v[82:85]
	v_mfma_f32_16x16x32_bf16 v[78:81], v[154:157], v[210:213], v[78:81]
	v_mfma_f32_16x16x32_bf16 v[74:77], v[170:173], v[210:213], v[74:77]
	v_mfma_f32_16x16x32_bf16 v[70:73], v[154:157], v[218:221], v[70:73]
	v_mfma_f32_16x16x32_bf16 v[66:69], v[170:173], v[218:221], v[66:69]
	s_setprio 0
	s_setprio 1
	v_mfma_f32_16x16x32_bf16 v[30:33], v[174:177], v[190:193], v[30:33]
	v_mfma_f32_16x16x32_bf16 v[26:29], v[182:185], v[190:193], v[26:29]
	v_mfma_f32_16x16x32_bf16 v[22:25], v[174:177], v[198:201], v[22:25]
	v_mfma_f32_16x16x32_bf16 v[18:21], v[182:185], v[198:201], v[18:21]
	v_mfma_f32_16x16x32_bf16 v[14:17], v[174:177], v[206:209], v[14:17]
	v_mfma_f32_16x16x32_bf16 v[10:13], v[182:185], v[206:209], v[10:13]
	v_mfma_f32_16x16x32_bf16 v[6:9], v[174:177], v[214:217], v[6:9]
	v_mfma_f32_16x16x32_bf16 v[2:5], v[182:185], v[214:217], v[2:5]
	v_mfma_f32_16x16x32_bf16 v[30:33], v[178:181], v[194:197], v[30:33]
	v_mfma_f32_16x16x32_bf16 v[26:29], v[186:189], v[194:197], v[26:29]
	v_mfma_f32_16x16x32_bf16 v[22:25], v[178:181], v[202:205], v[22:25]
	v_mfma_f32_16x16x32_bf16 v[18:21], v[186:189], v[202:205], v[18:21]
	v_mfma_f32_16x16x32_bf16 v[14:17], v[178:181], v[210:213], v[14:17]
	v_mfma_f32_16x16x32_bf16 v[10:13], v[186:189], v[210:213], v[10:13]
	v_mfma_f32_16x16x32_bf16 v[6:9], v[178:181], v[218:221], v[6:9]
	v_mfma_f32_16x16x32_bf16 v[2:5], v[186:189], v[218:221], v[2:5]
	s_setprio 0
	s_barrier
	s_add_i32 s66, 0, 0x18000
	v_add_u32_e32 v138, s66, v149
	s_add_i32 s67, 0, 0x1c000
	ds_read_b128 v[150:153], v138
	ds_read_b128 v[154:157], v138 offset:1024
	ds_read_b128 v[166:169], v138 offset:2048
	ds_read_b128 v[170:173], v138 offset:3072
	v_add_u32_e32 v138, s67, v149
	ds_read_b128 v[174:177], v138
	ds_read_b128 v[178:181], v138 offset:1024
	ds_read_b128 v[182:185], v138 offset:2048
	ds_read_b128 v[186:189], v138 offset:3072
	s_add_u32 s24, s24, 0x360000
	s_addc_u32 s25, s25, 0
	s_mov_b32 m0, s38
	v_lshl_add_u64 v[232:233], s[24:25], 0, v[136:137]
	ds_read_b128 v[190:193], v163 offset:32768
	ds_read_b128 v[194:197], v163 offset:33792
	ds_read_b128 v[198:201], v163 offset:34816
	ds_read_b128 v[202:205], v163 offset:35840
	ds_read_b128 v[206:209], v163 offset:36864
	ds_read_b128 v[210:213], v163 offset:37888
	ds_read_b128 v[214:217], v163 offset:38912
	ds_read_b128 v[218:221], v163 offset:39936
	global_load_lds_dwordx4 v[232:233], off
	v_lshl_add_u64 v[232:233], s[24:25], 0, v[132:133]
	s_mov_b32 m0, s39
	s_nop 0
	global_load_lds_dwordx4 v[232:233], off
	s_waitcnt vmcnt(12)
	s_waitcnt lgkmcnt(0)
	s_barrier
	s_setprio 1
	s_waitcnt lgkmcnt(0)
	v_mfma_f32_16x16x32_bf16 v[126:129], v[150:153], v[190:193], v[126:129]
	v_mfma_f32_16x16x32_bf16 v[122:125], v[166:169], v[190:193], v[122:125]
	v_mfma_f32_16x16x32_bf16 v[118:121], v[150:153], v[198:201], v[118:121]
	v_mfma_f32_16x16x32_bf16 v[114:117], v[166:169], v[198:201], v[114:117]
	v_mfma_f32_16x16x32_bf16 v[110:113], v[150:153], v[206:209], v[110:113]
	v_mfma_f32_16x16x32_bf16 v[106:109], v[166:169], v[206:209], v[106:109]
	v_mfma_f32_16x16x32_bf16 v[102:105], v[150:153], v[214:217], v[102:105]
	v_mfma_f32_16x16x32_bf16 v[98:101], v[166:169], v[214:217], v[98:101]
	v_mfma_f32_16x16x32_bf16 v[126:129], v[154:157], v[194:197], v[126:129]
	v_mfma_f32_16x16x32_bf16 v[122:125], v[170:173], v[194:197], v[122:125]
	v_mfma_f32_16x16x32_bf16 v[118:121], v[154:157], v[202:205], v[118:121]
	v_mfma_f32_16x16x32_bf16 v[114:117], v[170:173], v[202:205], v[114:117]
	v_mfma_f32_16x16x32_bf16 v[110:113], v[154:157], v[210:213], v[110:113]
	v_mfma_f32_16x16x32_bf16 v[106:109], v[170:173], v[210:213], v[106:109]
	v_mfma_f32_16x16x32_bf16 v[102:105], v[154:157], v[218:221], v[102:105]
	v_mfma_f32_16x16x32_bf16 v[98:101], v[170:173], v[218:221], v[98:101]
	s_setprio 0
	s_setprio 1
	v_mfma_f32_16x16x32_bf16 v[62:65], v[174:177], v[190:193], v[62:65]
	v_mfma_f32_16x16x32_bf16 v[58:61], v[182:185], v[190:193], v[58:61]
	v_mfma_f32_16x16x32_bf16 v[54:57], v[174:177], v[198:201], v[54:57]
	v_mfma_f32_16x16x32_bf16 v[50:53], v[182:185], v[198:201], v[50:53]
	v_mfma_f32_16x16x32_bf16 v[46:49], v[174:177], v[206:209], v[46:49]
	v_mfma_f32_16x16x32_bf16 v[42:45], v[182:185], v[206:209], v[42:45]
	v_mfma_f32_16x16x32_bf16 v[38:41], v[174:177], v[214:217], v[38:41]
	v_mfma_f32_16x16x32_bf16 v[34:37], v[182:185], v[214:217], v[34:37]
	v_mfma_f32_16x16x32_bf16 v[62:65], v[178:181], v[194:197], v[62:65]
	v_mfma_f32_16x16x32_bf16 v[58:61], v[186:189], v[194:197], v[58:61]
	v_mfma_f32_16x16x32_bf16 v[54:57], v[178:181], v[202:205], v[54:57]
	v_mfma_f32_16x16x32_bf16 v[50:53], v[186:189], v[202:205], v[50:53]
	v_mfma_f32_16x16x32_bf16 v[46:49], v[178:181], v[210:213], v[46:49]
	v_mfma_f32_16x16x32_bf16 v[42:45], v[186:189], v[210:213], v[42:45]
	v_mfma_f32_16x16x32_bf16 v[38:41], v[178:181], v[218:221], v[38:41]
	v_mfma_f32_16x16x32_bf16 v[34:37], v[186:189], v[218:221], v[34:37]
	s_setprio 0
	s_barrier
; #define PG8_STAGE(bufoff, gbase, voff) do { _Pragma("unroll") for (int _i = 0; _i < 2; ++_i) \
;         __builtin_amdgcn_global_load_lds((const unsigned*)((const char*)(gbase) + (voff)[_i]), (PG8_LAS unsigned*)(lds + (bufoff) + ldsw + _i * 8192), 16, 0, 0); } while (0)
; #define PG8_LDA(dst, b, h) do { _Pragma("unroll") for (int m = 0; m < 4; ++m) _Pragma("unroll") for (int k = 0; k < 2; ++k) dst[m][k] = *(const PG8_LAS bf16x8*)(lds + PG8_SA(b, h) + aoff + m * 2048 + k * 1024); } while (0)
; #define PG8_MMA(ai, bj, At, Bt) do { __builtin_amdgcn_s_setprio(1); _Pragma("unroll") for (int m = 0; m < 4; ++m) _Pragma("unroll") for (int n = 0; n < 2; ++n) _Pragma("unroll") for (int k = 0; k < 2; ++k) \
;         acc[ai][bj][m][n] = __builtin_amdgcn_mfma_f32_16x16x32_bf16(Bt[n][k], At[m][k], acc[ai][bj][m][n], 0, 0, 0); __builtin_amdgcn_s_setprio(0); } while (0)
; #define PG8_WAIT_V(n) asm volatile("s_waitcnt vmcnt(" #n ")" ::: "memory")
; #define PG8_WAIT_L(n) asm volatile("s_waitcnt lgkmcnt(" #n ")" ::: "memory")
; #define PG8_BAR __builtin_amdgcn_s_barrier()
; #define PG8_SCHED __builtin_amdgcn_sched_barrier(0)
; template <class Epi, class Sched, bool ALIGN_EPI = false, bool SP2 = false>
; __device__ __forceinline__ void gemm_phase(PG8_LAS unsigned char* lds, const Gemm g, const Sched& S, const Epi& E) {
;     ...
;         for (int t = 0; t < nt; t += 2) {
;     ...
;             PG8_LDA(At, 1, 1); PG8_STAGE(PG8_SB(1, 0), b3, voffB); PG8_STAGE(PG8_SB(1, 1), b3 + hstepB, voffB); PG8_STAGE(PG8_SA(1, 0), a3, voffA);
;             PG8_WAIT_V(8); PG8_WAIT_L(0); PG8_BAR; PG8_MMA(1, 0, At, B0); PG8_MMA(1, 1, At, B1); PG8_BAR; PG8_SCHED;
	s_add_i32 s24, s66, s21
	v_lshl_add_u64 v[158:159], v[158:159], 0, s[14:15]
	s_mov_b32 m0, s24
	ds_read_b128 v[190:193], v163 offset:49152
	ds_read_b128 v[194:197], v163 offset:50176
	ds_read_b128 v[198:201], v163 offset:51200
	ds_read_b128 v[202:205], v163 offset:52224
	ds_read_b128 v[206:209], v163 offset:53248
	ds_read_b128 v[210:213], v163 offset:54272
	ds_read_b128 v[214:217], v163 offset:55296
	ds_read_b128 v[218:221], v163 offset:56320
	global_load_lds_dwordx4 v[158:159], off
	v_lshl_add_u64 v[158:159], v[222:223], 0, s[14:15]
	s_add_i32 m0, s24, 0x2000
	s_add_i32 s24, s67, s21
	global_load_lds_dwordx4 v[158:159], off
	v_lshl_add_u64 v[158:159], v[224:225], 0, s[14:15]
	s_mov_b32 m0, s24
	s_nop 0
	global_load_lds_dwordx4 v[158:159], off
	v_lshl_add_u64 v[158:159], v[226:227], 0, s[14:15]
	s_add_i32 m0, s24, 0x2000
	s_nop 0
	global_load_lds_dwordx4 v[158:159], off
	v_lshl_add_u64 v[158:159], v[228:229], 0, s[14:15]
	s_mov_b32 m0, s42
	s_nop 0
	global_load_lds_dwordx4 v[158:159], off
	v_lshl_add_u64 v[158:159], v[230:231], 0, s[14:15]
	s_mov_b32 m0, s43
	s_nop 0
	global_load_lds_dwordx4 v[158:159], off
	s_waitcnt vmcnt(8)
	s_waitcnt lgkmcnt(0)
	s_barrier
	s_setprio 1
	s_waitcnt lgkmcnt(0)
	v_mfma_f32_16x16x32_bf16 v[94:97], v[150:153], v[190:193], v[94:97]
	v_mfma_f32_16x16x32_bf16 v[90:93], v[166:169], v[190:193], v[90:93]
	v_mfma_f32_16x16x32_bf16 v[86:89], v[150:153], v[198:201], v[86:89]
	v_mfma_f32_16x16x32_bf16 v[82:85], v[166:169], v[198:201], v[82:85]
	v_mfma_f32_16x16x32_bf16 v[78:81], v[150:153], v[206:209], v[78:81]
	v_mfma_f32_16x16x32_bf16 v[74:77], v[166:169], v[206:209], v[74:77]
	v_mfma_f32_16x16x32_bf16 v[70:73], v[150:153], v[214:217], v[70:73]
	v_mfma_f32_16x16x32_bf16 v[66:69], v[166:169], v[214:217], v[66:69]
	v_mfma_f32_16x16x32_bf16 v[94:97], v[154:157], v[194:197], v[94:97]
	v_mfma_f32_16x16x32_bf16 v[90:93], v[170:173], v[194:197], v[90:93]
	v_mfma_f32_16x16x32_bf16 v[86:89], v[154:157], v[202:205], v[86:89]
	v_mfma_f32_16x16x32_bf16 v[82:85], v[170:173], v[202:205], v[82:85]
	v_mfma_f32_16x16x32_bf16 v[78:81], v[154:157], v[210:213], v[78:81]
	v_mfma_f32_16x16x32_bf16 v[74:77], v[170:173], v[210:213], v[74:77]
	v_mfma_f32_16x16x32_bf16 v[70:73], v[154:157], v[218:221], v[70:73]
	v_mfma_f32_16x16x32_bf16 v[66:69], v[170:173], v[218:221], v[66:69]
	s_setprio 0
	s_setprio 1
	v_mfma_f32_16x16x32_bf16 v[30:33], v[174:177], v[190:193], v[30:33]
	v_mfma_f32_16x16x32_bf16 v[26:29], v[182:185], v[190:193], v[26:29]
	v_mfma_f32_16x16x32_bf16 v[22:25], v[174:177], v[198:201], v[22:25]
	v_mfma_f32_16x16x32_bf16 v[18:21], v[182:185], v[198:201], v[18:21]
	v_mfma_f32_16x16x32_bf16 v[14:17], v[174:177], v[206:209], v[14:17]
	v_mfma_f32_16x16x32_bf16 v[10:13], v[182:185], v[206:209], v[10:13]
	v_mfma_f32_16x16x32_bf16 v[6:9], v[174:177], v[214:217], v[6:9]
	v_mfma_f32_16x16x32_bf16 v[2:5], v[182:185], v[214:217], v[2:5]
	v_mfma_f32_16x16x32_bf16 v[30:33], v[178:181], v[194:197], v[30:33]
	v_mfma_f32_16x16x32_bf16 v[26:29], v[186:189], v[194:197], v[26:29]
	v_mfma_f32_16x16x32_bf16 v[22:25], v[178:181], v[202:205], v[22:25]
	v_mfma_f32_16x16x32_bf16 v[18:21], v[186:189], v[202:205], v[18:21]
	v_mfma_f32_16x16x32_bf16 v[14:17], v[178:181], v[210:213], v[14:17]
	v_mfma_f32_16x16x32_bf16 v[10:13], v[186:189], v[210:213], v[10:13]
	v_mfma_f32_16x16x32_bf16 v[6:9], v[178:181], v[218:221], v[6:9]
	v_mfma_f32_16x16x32_bf16 v[2:5], v[186:189], v[218:221], v[2:5]
	s_setprio 0
	s_barrier
	s_add_u32 s73, s73, 0x100
	s_addc_u32 s74, s74, 0
	s_cmp_ge_i32 s75, s41
	s_mov_b64 s[66:67], s[68:69]
	s_mov_b32 s24, s75
	s_cbranch_scc0 .LBB0_524

; #define GAS __attribute__((address_space(1)))
; __device__ __forceinline__ v4u pack8(const float (&f)[8]) { v4u w; w.x = pk2(f[0], f[1]); w.y = pk2(f[2], f[3]); w.z = pk2(f[4], f[5]); w.w = pk2(f[6], f[7]); return w; }
; __device__ __forceinline__ float fexp2(float x) { return __builtin_amdgcn_exp2f(x); }
; __device__ __forceinline__ float frcp(float x) { return __builtin_amdgcn_rcpf(x); }
;     __device__ __forceinline__ void operator()(const af4 (&acc)[2][2][4][2], const pg8::Unit& u, int wr, int wc, int fr, int fq) const {
;         const int kind = u.pn >> 3, dir = kind & 1, cb = (u.pn & 7) * 256 + wc * 32 + 8 * fq, row0 = u.pm * 256 + wr * 64 + fr;
;         const float* bias = (kind < 2 ? w0 : a0) + dir * BW;
;         const float sc = kind < 2 ? 0.6065306597126334f * 1.4426950408889634f : 1.0f;
; #pragma unroll
;         for (int bj = 0; bj < 2; ++bj) {
;             const int c = cb + bj * 128;
;             const af4 bb[2] = {*(const GAS af4*)(bias + c) * -1.4426950408889634f, *(const GAS af4*)(bias + c + 4) * -1.4426950408889634f};
; #pragma unroll
;             for (int ai = 0; ai < 2; ++ai)
; #pragma unroll
;                 for (int m = 0; m < 4; ++m) {
;                     const int row = row0 + ai * 128 + m * 16;
;                     float o[8];
; #pragma unroll
;                     for (int n = 0; n < 2; ++n)
; #pragma unroll
;                         for (int e = 0; e < 4; e += 2) {
;                             const f32x2 x = {acc[ai][bj][m][n][e], acc[ai][bj][m][n][e + 1]};
;                             const f32x2 ar = x * -1.4426950408889634f + (f32x2){bb[n][e], bb[n][e + 1]};
;                             const f32x2 den = (f32x2){fexp2(ar.x), fexp2(ar.y)} + 1.0f;
;                             const f32x2 r = (f32x2){frcp(den.x), frcp(den.y)} * sc;
;                             o[4 * n + e] = r.x; o[4 * n + e + 1] = r.y; }
;                     *(GAS v4u*)(EA + ((size_t)kind * MALL + row) * BW + c) = pack8(o);
.LBB0_527:
	s_lshl_b32 s25, s49, 8
	s_ashr_i32 s24, s49, 3
	s_and_b32 s25, s25, 0x700
	s_cmp_lt_i32 s24, 2
	v_lshl_add_u32 v150, s72, 8, v1
	s_cselect_b64 vcc, -1, 0
	v_readlane_b32 s72, v254, 20
	s_and_b64 s[66:67], vcc, exec
	v_readlane_b32 s78, v254, 26
	v_readlane_b32 s79, v254, 27
	v_readlane_b32 s82, v254, 30
	v_readlane_b32 s83, v254, 31
	v_or_b32_e32 v138, s25, v160
	s_cselect_b32 s25, s79, s83
	s_cselect_b32 s49, s78, s82
	s_lshl_b32 s66, s24, 13
	s_and_b32 s66, s66, 0x2000
	s_add_u32 s66, s49, s66
	s_addc_u32 s67, s25, 0
	v_lshlrev_b32_e32 v166, 2, v138
	v_mov_b64_e32 v[168:169], v[234:235]
	v_mov_b64_e32 v[170:171], v[236:237]
	v_mov_b64_e32 v[152:153], v[238:239]
	v_mov_b64_e32 v[154:155], v[240:241]
	v_cndmask_b32_e32 v148, 1.0, v164, vcc
	v_ashrrev_i32_e32 v151, 31, v150
	v_lshlrev_b32_e32 v138, 1, v138
	s_and_b64 vcc, exec, s[4:5]
	v_readlane_b32 s73, v254, 21
	v_readlane_b32 s74, v254, 22
	v_readlane_b32 s75, v254, 23
	v_readlane_b32 s76, v254, 24
	v_readlane_b32 s77, v254, 25
	v_readlane_b32 s80, v254, 28
	v_readlane_b32 s81, v254, 29
	v_readlane_b32 s84, v254, 32
	v_readlane_b32 s85, v254, 33
	v_readlane_b32 s86, v254, 34
	v_readlane_b32 s87, v254, 35
	s_nop 0
	v_pk_mul_f32 v[156:157], v[154:155], s[20:21] op_sel_hi:[1,0]
	v_pk_mul_f32 v[158:159], v[152:153], s[20:21] op_sel_hi:[1,0]
	v_pk_mul_f32 v[154:155], v[168:169], s[20:21] op_sel_hi:[1,0]
	v_pk_mul_f32 v[152:153], v[170:171], s[20:21] op_sel_hi:[1,0]
	v_pk_fma_f32 v[126:127], v[126:127], s[22:23], v[158:159] op_sel_hi:[1,0,1] neg_lo:[1,0,0] neg_hi:[1,0,0]
	v_pk_fma_f32 v[122:123], v[122:123], s[22:23], v[154:155] op_sel_hi:[1,0,1] neg_lo:[1,0,0] neg_hi:[1,0,0]
	v_exp_f32_e32 v126, v126
	v_exp_f32_e32 v127, v127
	v_pk_fma_f32 v[128:129], v[128:129], s[22:23], v[156:157] op_sel_hi:[1,0,1] neg_lo:[1,0,0] neg_hi:[1,0,0]
	v_exp_f32_e32 v122, v122
	v_exp_f32_e32 v123, v123
	v_pk_fma_f32 v[124:125], v[124:125], s[22:23], v[152:153] op_sel_hi:[1,0,1] neg_lo:[1,0,0] neg_hi:[1,0,0]
	v_exp_f32_e32 v128, v128
	v_exp_f32_e32 v129, v129
	v_exp_f32_e32 v124, v124
	v_exp_f32_e32 v125, v125
	v_pk_add_f32 v[126:127], v[126:127], 1.0 op_sel_hi:[1,0]
	v_pk_add_f32 v[122:123], v[122:123], 1.0 op_sel_hi:[1,0]
	v_rcp_f32_e32 v126, v126
	v_rcp_f32_e32 v127, v127
	v_pk_add_f32 v[128:129], v[128:129], 1.0 op_sel_hi:[1,0]
	v_rcp_f32_e32 v122, v122
	v_rcp_f32_e32 v123, v123
	v_pk_add_f32 v[124:125], v[124:125], 1.0 op_sel_hi:[1,0]
	v_pk_fma_f32 v[118:119], v[118:119], s[22:23], v[158:159] op_sel_hi:[1,0,1] neg_lo:[1,0,0] neg_hi:[1,0,0]
	v_pk_fma_f32 v[114:115], v[114:115], s[22:23], v[154:155] op_sel_hi:[1,0,1] neg_lo:[1,0,0] neg_hi:[1,0,0]
	v_rcp_f32_e32 v128, v128
	v_rcp_f32_e32 v129, v129
	v_rcp_f32_e32 v124, v124
	v_rcp_f32_e32 v125, v125
	v_exp_f32_e32 v118, v118
	v_exp_f32_e32 v119, v119
	v_pk_fma_f32 v[120:121], v[120:121], s[22:23], v[156:157] op_sel_hi:[1,0,1] neg_lo:[1,0,0] neg_hi:[1,0,0]
	v_exp_f32_e32 v114, v114
	v_exp_f32_e32 v115, v115
	v_pk_fma_f32 v[116:117], v[116:117], s[22:23], v[152:153] op_sel_hi:[1,0,1] neg_lo:[1,0,0] neg_hi:[1,0,0]
	v_exp_f32_e32 v120, v120
	v_exp_f32_e32 v121, v121
	v_exp_f32_e32 v116, v116
	v_exp_f32_e32 v117, v117
	v_pk_mul_f32 v[126:127], v[148:149], v[126:127] op_sel_hi:[0,1]
	v_pk_mul_f32 v[122:123], v[148:149], v[122:123] op_sel_hi:[0,1]
	v_pk_mul_f32 v[128:129], v[148:149], v[128:129] op_sel_hi:[0,1]
	v_pk_mul_f32 v[168:169], v[148:149], v[124:125] op_sel_hi:[0,1]
	v_cvt_pk_bf16_f32 v124, v126, v127
	v_cvt_pk_bf16_f32 v125, v128, v129
	v_cvt_pk_bf16_f32 v126, v122, v123
	v_mad_i64_i32 v[122:123], s[68:69], s24, v165, v[150:151]
	v_pk_add_f32 v[118:119], v[118:119], 1.0 op_sel_hi:[1,0]
	v_pk_add_f32 v[114:115], v[114:115], 1.0 op_sel_hi:[1,0]
	v_lshlrev_b64 v[122:123], 12, v[122:123]
	v_rcp_f32_e32 v118, v118
	v_rcp_f32_e32 v119, v119
	v_pk_add_f32 v[120:121], v[120:121], 1.0 op_sel_hi:[1,0]
	v_rcp_f32_e32 v114, v114
	v_rcp_f32_e32 v115, v115
	v_pk_add_f32 v[116:117], v[116:117], 1.0 op_sel_hi:[1,0]
	v_pk_fma_f32 v[110:111], v[110:111], s[22:23], v[158:159] op_sel_hi:[1,0,1] neg_lo:[1,0,0] neg_hi:[1,0,0]
	v_pk_fma_f32 v[106:107], v[106:107], s[22:23], v[154:155] op_sel_hi:[1,0,1] neg_lo:[1,0,0] neg_hi:[1,0,0]
	v_lshl_add_u64 v[122:123], s[56:57], 0, v[122:123]
	v_rcp_f32_e32 v120, v120
	v_rcp_f32_e32 v121, v121
	v_rcp_f32_e32 v116, v116
	v_rcp_f32_e32 v117, v117
	v_exp_f32_e32 v110, v110
	v_exp_f32_e32 v111, v111
	v_pk_fma_f32 v[112:113], v[112:113], s[22:23], v[156:157] op_sel_hi:[1,0,1] neg_lo:[1,0,0] neg_hi:[1,0,0]
	v_exp_f32_e32 v106, v106
	v_exp_f32_e32 v107, v107
	v_pk_fma_f32 v[108:109], v[108:109], s[22:23], v[152:153] op_sel_hi:[1,0,1] neg_lo:[1,0,0] neg_hi:[1,0,0]
	v_lshl_add_u64 v[122:123], v[122:123], 0, v[138:139]
	v_exp_f32_e32 v112, v112
	v_exp_f32_e32 v113, v113
	v_exp_f32_e32 v108, v108
	v_exp_f32_e32 v109, v109
	v_cvt_pk_bf16_f32 v127, v168, v169
	global_store_dwordx4 v[122:123], v[124:127], off
	v_pk_mul_f32 v[118:119], v[148:149], v[118:119] op_sel_hi:[0,1]
	v_pk_mul_f32 v[114:115], v[148:149], v[114:115] op_sel_hi:[0,1]
	v_or_b32_e32 v126, 16, v150
	v_ashrrev_i32_e32 v127, 31, v126
	v_pk_mul_f32 v[120:121], v[148:149], v[120:121] op_sel_hi:[0,1]
	v_pk_mul_f32 v[124:125], v[148:149], v[116:117] op_sel_hi:[0,1]
	v_cvt_pk_bf16_f32 v116, v118, v119
	v_cvt_pk_bf16_f32 v117, v120, v121
	v_cvt_pk_bf16_f32 v118, v114, v115
	v_mad_i64_i32 v[114:115], s[68:69], s24, v165, v[126:127]
	v_pk_add_f32 v[110:111], v[110:111], 1.0 op_sel_hi:[1,0]
	v_pk_add_f32 v[106:107], v[106:107], 1.0 op_sel_hi:[1,0]
	v_lshlrev_b64 v[114:115], 12, v[114:115]
	v_rcp_f32_e32 v110, v110
	v_rcp_f32_e32 v111, v111
	v_pk_add_f32 v[112:113], v[112:113], 1.0 op_sel_hi:[1,0]
; #define GAS __attribute__((address_space(1)))
; __device__ __forceinline__ v4u pack8(const float (&f)[8]) { v4u w; w.x = pk2(f[0], f[1]); w.y = pk2(f[2], f[3]); w.z = pk2(f[4], f[5]); w.w = pk2(f[6], f[7]); return w; }
; __device__ __forceinline__ float fexp2(float x) { return __builtin_amdgcn_exp2f(x); }
; __device__ __forceinline__ float frcp(float x) { return __builtin_amdgcn_rcpf(x); }
;     __device__ __forceinline__ void operator()(const af4 (&acc)[2][2][4][2], const pg8::Unit& u, int wr, int wc, int fr, int fq) const {
;     ...
;             for (int ai = 0; ai < 2; ++ai)
; #pragma unroll
;                 for (int m = 0; m < 4; ++m) {
;                     const int row = row0 + ai * 128 + m * 16;
;                     float o[8];
; #pragma unroll
;                     for (int n = 0; n < 2; ++n)
; #pragma unroll
;                         for (int e = 0; e < 4; e += 2) {
;                             const f32x2 x = {acc[ai][bj][m][n][e], acc[ai][bj][m][n][e + 1]};
;                             const f32x2 ar = x * -1.4426950408889634f + (f32x2){bb[n][e], bb[n][e + 1]};
;                             const f32x2 den = (f32x2){fexp2(ar.x), fexp2(ar.y)} + 1.0f;
;                             const f32x2 r = (f32x2){frcp(den.x), frcp(den.y)} * sc;
;                             o[4 * n + e] = r.x; o[4 * n + e + 1] = r.y; }
;                     *(GAS v4u*)(EA + ((size_t)kind * MALL + row) * BW + c) = pack8(o);
	v_rcp_f32_e32 v106, v106
	v_rcp_f32_e32 v107, v107
	v_pk_add_f32 v[108:109], v[108:109], 1.0 op_sel_hi:[1,0]
	v_pk_fma_f32 v[102:103], v[102:103], s[22:23], v[158:159] op_sel_hi:[1,0,1] neg_lo:[1,0,0] neg_hi:[1,0,0]
	v_pk_fma_f32 v[98:99], v[98:99], s[22:23], v[154:155] op_sel_hi:[1,0,1] neg_lo:[1,0,0] neg_hi:[1,0,0]
	v_lshl_add_u64 v[114:115], s[56:57], 0, v[114:115]
	v_rcp_f32_e32 v112, v112
	v_rcp_f32_e32 v113, v113
	v_rcp_f32_e32 v108, v108
	v_rcp_f32_e32 v109, v109
	v_exp_f32_e32 v102, v102
	v_exp_f32_e32 v103, v103
	v_pk_fma_f32 v[104:105], v[104:105], s[22:23], v[156:157] op_sel_hi:[1,0,1] neg_lo:[1,0,0] neg_hi:[1,0,0]
	v_exp_f32_e32 v98, v98
	v_exp_f32_e32 v99, v99
	v_pk_fma_f32 v[100:101], v[100:101], s[22:23], v[152:153] op_sel_hi:[1,0,1] neg_lo:[1,0,0] neg_hi:[1,0,0]
	v_lshl_add_u64 v[114:115], v[114:115], 0, v[138:139]
	v_exp_f32_e32 v104, v104
	v_exp_f32_e32 v105, v105
	v_exp_f32_e32 v100, v100
	v_exp_f32_e32 v101, v101
	v_cvt_pk_bf16_f32 v119, v124, v125
	global_store_dwordx4 v[114:115], v[116:119], off
	v_pk_mul_f32 v[110:111], v[148:149], v[110:111] op_sel_hi:[0,1]
	v_pk_mul_f32 v[106:107], v[148:149], v[106:107] op_sel_hi:[0,1]
	v_or_b32_e32 v118, 32, v150
	v_ashrrev_i32_e32 v119, 31, v118
	v_pk_mul_f32 v[112:113], v[148:149], v[112:113] op_sel_hi:[0,1]
	v_pk_mul_f32 v[116:117], v[148:149], v[108:109] op_sel_hi:[0,1]
	v_cvt_pk_bf16_f32 v108, v110, v111
	v_cvt_pk_bf16_f32 v109, v112, v113
	v_cvt_pk_bf16_f32 v110, v106, v107
	v_mad_i64_i32 v[106:107], s[68:69], s24, v165, v[118:119]
	v_pk_add_f32 v[102:103], v[102:103], 1.0 op_sel_hi:[1,0]
	v_pk_add_f32 v[98:99], v[98:99], 1.0 op_sel_hi:[1,0]
	v_lshlrev_b64 v[106:107], 12, v[106:107]
	v_rcp_f32_e32 v102, v102
	v_rcp_f32_e32 v103, v103
	v_pk_add_f32 v[104:105], v[104:105], 1.0 op_sel_hi:[1,0]
	v_rcp_f32_e32 v98, v98
	v_rcp_f32_e32 v99, v99
	v_pk_add_f32 v[100:101], v[100:101], 1.0 op_sel_hi:[1,0]
	v_pk_fma_f32 v[94:95], v[94:95], s[22:23], v[158:159] op_sel_hi:[1,0,1] neg_lo:[1,0,0] neg_hi:[1,0,0]
	v_pk_fma_f32 v[90:91], v[90:91], s[22:23], v[154:155] op_sel_hi:[1,0,1] neg_lo:[1,0,0] neg_hi:[1,0,0]
	v_lshl_add_u64 v[106:107], s[56:57], 0, v[106:107]
	v_rcp_f32_e32 v104, v104
	v_rcp_f32_e32 v105, v105
	v_rcp_f32_e32 v100, v100
	v_rcp_f32_e32 v101, v101
	v_exp_f32_e32 v94, v94
	v_exp_f32_e32 v95, v95
	v_pk_fma_f32 v[96:97], v[96:97], s[22:23], v[156:157] op_sel_hi:[1,0,1] neg_lo:[1,0,0] neg_hi:[1,0,0]
	v_exp_f32_e32 v90, v90
	v_exp_f32_e32 v91, v91
	v_pk_fma_f32 v[92:93], v[92:93], s[22:23], v[152:153] op_sel_hi:[1,0,1] neg_lo:[1,0,0] neg_hi:[1,0,0]
	v_lshl_add_u64 v[106:107], v[106:107], 0, v[138:139]
	v_exp_f32_e32 v96, v96
	v_exp_f32_e32 v97, v97
	v_exp_f32_e32 v92, v92
	v_exp_f32_e32 v93, v93
	v_cvt_pk_bf16_f32 v111, v116, v117
	global_store_dwordx4 v[106:107], v[108:111], off
	v_pk_mul_f32 v[102:103], v[148:149], v[102:103] op_sel_hi:[0,1]
	v_pk_mul_f32 v[98:99], v[148:149], v[98:99] op_sel_hi:[0,1]
	v_or_b32_e32 v110, 48, v150
	v_ashrrev_i32_e32 v111, 31, v110
	v_pk_mul_f32 v[104:105], v[148:149], v[104:105] op_sel_hi:[0,1]
	v_pk_mul_f32 v[108:109], v[148:149], v[100:101] op_sel_hi:[0,1]
	v_cvt_pk_bf16_f32 v100, v102, v103
	v_cvt_pk_bf16_f32 v101, v104, v105
	v_cvt_pk_bf16_f32 v102, v98, v99
	v_mad_i64_i32 v[98:99], s[68:69], s24, v165, v[110:111]
	v_pk_add_f32 v[94:95], v[94:95], 1.0 op_sel_hi:[1,0]
	v_pk_add_f32 v[90:91], v[90:91], 1.0 op_sel_hi:[1,0]
	v_lshlrev_b64 v[98:99], 12, v[98:99]
	v_rcp_f32_e32 v94, v94
	v_rcp_f32_e32 v95, v95
	v_pk_add_f32 v[96:97], v[96:97], 1.0 op_sel_hi:[1,0]
	v_rcp_f32_e32 v90, v90
	v_rcp_f32_e32 v91, v91
	v_pk_add_f32 v[92:93], v[92:93], 1.0 op_sel_hi:[1,0]
	v_pk_fma_f32 v[86:87], v[86:87], s[22:23], v[158:159] op_sel_hi:[1,0,1] neg_lo:[1,0,0] neg_hi:[1,0,0]
	v_pk_fma_f32 v[82:83], v[82:83], s[22:23], v[154:155] op_sel_hi:[1,0,1] neg_lo:[1,0,0] neg_hi:[1,0,0]
	v_lshl_add_u64 v[98:99], s[56:57], 0, v[98:99]
	v_rcp_f32_e32 v96, v96
	v_rcp_f32_e32 v97, v97
	v_rcp_f32_e32 v92, v92
	v_rcp_f32_e32 v93, v93
	v_exp_f32_e32 v86, v86
	v_exp_f32_e32 v87, v87
	v_pk_fma_f32 v[88:89], v[88:89], s[22:23], v[156:157] op_sel_hi:[1,0,1] neg_lo:[1,0,0] neg_hi:[1,0,0]
	v_exp_f32_e32 v82, v82
	v_exp_f32_e32 v83, v83
	v_pk_fma_f32 v[84:85], v[84:85], s[22:23], v[152:153] op_sel_hi:[1,0,1] neg_lo:[1,0,0] neg_hi:[1,0,0]
	v_lshl_add_u64 v[98:99], v[98:99], 0, v[138:139]
	v_exp_f32_e32 v88, v88
	v_exp_f32_e32 v89, v89
	v_exp_f32_e32 v84, v84
	v_exp_f32_e32 v85, v85
	v_cvt_pk_bf16_f32 v103, v108, v109
	global_store_dwordx4 v[98:99], v[100:103], off
	v_pk_mul_f32 v[94:95], v[148:149], v[94:95] op_sel_hi:[0,1]
	v_pk_mul_f32 v[90:91], v[148:149], v[90:91] op_sel_hi:[0,1]
	v_add_u32_e32 v100, 0x80, v150
	v_ashrrev_i32_e32 v101, 31, v100
	v_pk_mul_f32 v[96:97], v[148:149], v[96:97] op_sel_hi:[0,1]
	v_pk_mul_f32 v[102:103], v[148:149], v[92:93] op_sel_hi:[0,1]
	v_cvt_pk_bf16_f32 v92, v94, v95
	v_cvt_pk_bf16_f32 v93, v96, v97
	v_cvt_pk_bf16_f32 v94, v90, v91
	v_mad_i64_i32 v[90:91], s[68:69], s24, v165, v[100:101]
	v_pk_add_f32 v[86:87], v[86:87], 1.0 op_sel_hi:[1,0]
	v_pk_add_f32 v[82:83], v[82:83], 1.0 op_sel_hi:[1,0]
	v_lshlrev_b64 v[90:91], 12, v[90:91]
	v_rcp_f32_e32 v86, v86
	v_rcp_f32_e32 v87, v87
	v_pk_add_f32 v[88:89], v[88:89], 1.0 op_sel_hi:[1,0]
	v_rcp_f32_e32 v82, v82
	v_rcp_f32_e32 v83, v83
	v_pk_add_f32 v[84:85], v[84:85], 1.0 op_sel_hi:[1,0]
	v_pk_fma_f32 v[78:79], v[78:79], s[22:23], v[158:159] op_sel_hi:[1,0,1] neg_lo:[1,0,0] neg_hi:[1,0,0]
	v_pk_fma_f32 v[74:75], v[74:75], s[22:23], v[154:155] op_sel_hi:[1,0,1] neg_lo:[1,0,0] neg_hi:[1,0,0]
	v_lshl_add_u64 v[90:91], s[56:57], 0, v[90:91]
	v_rcp_f32_e32 v88, v88
	v_rcp_f32_e32 v89, v89
; #define GAS __attribute__((address_space(1)))
; __device__ __forceinline__ v4u pack8(const float (&f)[8]) { v4u w; w.x = pk2(f[0], f[1]); w.y = pk2(f[2], f[3]); w.z = pk2(f[4], f[5]); w.w = pk2(f[6], f[7]); return w; }
; __device__ __forceinline__ float fexp2(float x) { return __builtin_amdgcn_exp2f(x); }
; __device__ __forceinline__ float frcp(float x) { return __builtin_amdgcn_rcpf(x); }
;     __device__ __forceinline__ void operator()(const af4 (&acc)[2][2][4][2], const pg8::Unit& u, int wr, int wc, int fr, int fq) const {
;     ...
;         for (int bj = 0; bj < 2; ++bj) {
;             const int c = cb + bj * 128;
;             const af4 bb[2] = {*(const GAS af4*)(bias + c) * -1.4426950408889634f, *(const GAS af4*)(bias + c + 4) * -1.4426950408889634f};
; #pragma unroll
;             for (int ai = 0; ai < 2; ++ai)
; #pragma unroll
;                 for (int m = 0; m < 4; ++m) {
;                     const int row = row0 + ai * 128 + m * 16;
;                     float o[8];
; #pragma unroll
;                     for (int n = 0; n < 2; ++n)
; #pragma unroll
;                         for (int e = 0; e < 4; e += 2) {
;                             const f32x2 x = {acc[ai][bj][m][n][e], acc[ai][bj][m][n][e + 1]};
;                             const f32x2 ar = x * -1.4426950408889634f + (f32x2){bb[n][e], bb[n][e + 1]};
;                             const f32x2 den = (f32x2){fexp2(ar.x), fexp2(ar.y)} + 1.0f;
;                             const f32x2 r = (f32x2){frcp(den.x), frcp(den.y)} * sc;
;                             o[4 * n + e] = r.x; o[4 * n + e + 1] = r.y; }
;                     *(GAS v4u*)(EA + ((size_t)kind * MALL + row) * BW + c) = pack8(o);
	v_rcp_f32_e32 v84, v84
	v_rcp_f32_e32 v85, v85
	v_exp_f32_e32 v78, v78
	v_exp_f32_e32 v79, v79
	v_pk_fma_f32 v[80:81], v[80:81], s[22:23], v[156:157] op_sel_hi:[1,0,1] neg_lo:[1,0,0] neg_hi:[1,0,0]
	v_exp_f32_e32 v74, v74
	v_exp_f32_e32 v75, v75
	v_pk_fma_f32 v[76:77], v[76:77], s[22:23], v[152:153] op_sel_hi:[1,0,1] neg_lo:[1,0,0] neg_hi:[1,0,0]
	v_lshl_add_u64 v[90:91], v[90:91], 0, v[138:139]
	v_exp_f32_e32 v80, v80
	v_exp_f32_e32 v81, v81
	v_exp_f32_e32 v76, v76
	v_exp_f32_e32 v77, v77
	v_cvt_pk_bf16_f32 v95, v102, v103
	global_store_dwordx4 v[90:91], v[92:95], off
	v_pk_mul_f32 v[86:87], v[148:149], v[86:87] op_sel_hi:[0,1]
	v_pk_mul_f32 v[82:83], v[148:149], v[82:83] op_sel_hi:[0,1]
	v_add_u32_e32 v94, 0x90, v150
	v_ashrrev_i32_e32 v95, 31, v94
	v_pk_mul_f32 v[88:89], v[148:149], v[88:89] op_sel_hi:[0,1]
	v_pk_mul_f32 v[92:93], v[148:149], v[84:85] op_sel_hi:[0,1]
	v_cvt_pk_bf16_f32 v84, v86, v87
	v_cvt_pk_bf16_f32 v85, v88, v89
	v_cvt_pk_bf16_f32 v86, v82, v83
	v_mad_i64_i32 v[82:83], s[68:69], s24, v165, v[94:95]
	v_pk_add_f32 v[78:79], v[78:79], 1.0 op_sel_hi:[1,0]
	v_pk_add_f32 v[74:75], v[74:75], 1.0 op_sel_hi:[1,0]
	v_lshlrev_b64 v[82:83], 12, v[82:83]
	v_rcp_f32_e32 v78, v78
	v_rcp_f32_e32 v79, v79
	v_pk_add_f32 v[80:81], v[80:81], 1.0 op_sel_hi:[1,0]
	v_rcp_f32_e32 v74, v74
	v_rcp_f32_e32 v75, v75
	v_pk_add_f32 v[76:77], v[76:77], 1.0 op_sel_hi:[1,0]
	v_pk_fma_f32 v[70:71], v[70:71], s[22:23], v[158:159] op_sel_hi:[1,0,1] neg_lo:[1,0,0] neg_hi:[1,0,0]
	v_pk_fma_f32 v[66:67], v[66:67], s[22:23], v[154:155] op_sel_hi:[1,0,1] neg_lo:[1,0,0] neg_hi:[1,0,0]
	v_lshl_add_u64 v[82:83], s[56:57], 0, v[82:83]
	v_rcp_f32_e32 v80, v80
	v_rcp_f32_e32 v81, v81
	v_rcp_f32_e32 v76, v76
	v_rcp_f32_e32 v77, v77
	v_exp_f32_e32 v70, v70
	v_exp_f32_e32 v71, v71
	v_pk_fma_f32 v[72:73], v[72:73], s[22:23], v[156:157] op_sel_hi:[1,0,1] neg_lo:[1,0,0] neg_hi:[1,0,0]
	v_exp_f32_e32 v66, v66
	v_exp_f32_e32 v67, v67
	v_pk_fma_f32 v[68:69], v[68:69], s[22:23], v[152:153] op_sel_hi:[1,0,1] neg_lo:[1,0,0] neg_hi:[1,0,0]
	v_lshl_add_u64 v[82:83], v[82:83], 0, v[138:139]
	v_exp_f32_e32 v72, v72
	v_exp_f32_e32 v73, v73
	v_exp_f32_e32 v68, v68
	v_exp_f32_e32 v69, v69
	v_cvt_pk_bf16_f32 v87, v92, v93
	global_store_dwordx4 v[82:83], v[84:87], off
	v_pk_mul_f32 v[78:79], v[148:149], v[78:79] op_sel_hi:[0,1]
	v_pk_mul_f32 v[74:75], v[148:149], v[74:75] op_sel_hi:[0,1]
	v_add_u32_e32 v86, 0xa0, v150
	v_ashrrev_i32_e32 v87, 31, v86
	v_pk_mul_f32 v[80:81], v[148:149], v[80:81] op_sel_hi:[0,1]
	v_pk_mul_f32 v[84:85], v[148:149], v[76:77] op_sel_hi:[0,1]
	v_cvt_pk_bf16_f32 v76, v78, v79
	v_cvt_pk_bf16_f32 v77, v80, v81
	v_cvt_pk_bf16_f32 v78, v74, v75
	v_mad_i64_i32 v[74:75], s[68:69], s24, v165, v[86:87]
	v_pk_add_f32 v[70:71], v[70:71], 1.0 op_sel_hi:[1,0]
	v_pk_add_f32 v[66:67], v[66:67], 1.0 op_sel_hi:[1,0]
	v_lshlrev_b64 v[74:75], 12, v[74:75]
	v_rcp_f32_e32 v70, v70
	v_rcp_f32_e32 v71, v71
	v_pk_add_f32 v[72:73], v[72:73], 1.0 op_sel_hi:[1,0]
	v_rcp_f32_e32 v66, v66
	v_rcp_f32_e32 v67, v67
	v_pk_add_f32 v[68:69], v[68:69], 1.0 op_sel_hi:[1,0]
	v_lshl_add_u64 v[74:75], s[56:57], 0, v[74:75]
	v_rcp_f32_e32 v72, v72
	v_rcp_f32_e32 v73, v73
	v_rcp_f32_e32 v68, v68
	v_rcp_f32_e32 v69, v69
	v_lshl_add_u64 v[74:75], v[74:75], 0, v[138:139]
	v_cvt_pk_bf16_f32 v79, v84, v85
	global_store_dwordx4 v[74:75], v[76:79], off
	v_pk_mul_f32 v[70:71], v[148:149], v[70:71] op_sel_hi:[0,1]
	v_pk_mul_f32 v[66:67], v[148:149], v[66:67] op_sel_hi:[0,1]
	v_add_u32_e32 v78, 0xb0, v150
	v_ashrrev_i32_e32 v79, 31, v78
	v_pk_mul_f32 v[72:73], v[148:149], v[72:73] op_sel_hi:[0,1]
	v_pk_mul_f32 v[76:77], v[148:149], v[68:69] op_sel_hi:[0,1]
	v_cvt_pk_bf16_f32 v68, v70, v71
	v_cvt_pk_bf16_f32 v69, v72, v73
	v_cvt_pk_bf16_f32 v70, v66, v67
	v_mad_i64_i32 v[66:67], s[24:25], s24, v165, v[78:79]
	v_lshlrev_b64 v[66:67], 12, v[66:67]
	v_lshl_add_u64 v[66:67], s[56:57], 0, v[66:67]
	v_lshl_add_u64 v[66:67], v[66:67], 0, v[138:139]
	v_cvt_pk_bf16_f32 v71, v76, v77
	global_store_dwordx4 v[66:67], v[68:71], off
	v_mov_b64_e32 v[78:79], v[242:243]
	v_mov_b64_e32 v[80:81], v[244:245]
	s_nop 0
	v_mov_b64_e32 v[68:69], v[246:247]
	v_mov_b64_e32 v[70:71], v[248:249]
	s_mov_b64 s[24:25], -1
	s_nop 0
	v_pk_mul_f32 v[72:73], v[70:71], s[20:21] op_sel_hi:[1,0]
	v_pk_mul_f32 v[70:71], v[78:79], s[20:21] op_sel_hi:[1,0]
	v_pk_mul_f32 v[76:77], v[68:69], s[20:21] op_sel_hi:[1,0]
	v_pk_fma_f32 v[58:59], v[58:59], s[22:23], v[70:71] op_sel_hi:[1,0,1] neg_lo:[1,0,0] neg_hi:[1,0,0]
	v_pk_mul_f32 v[68:69], v[80:81], s[20:21] op_sel_hi:[1,0]
	v_exp_f32_e32 v58, v58
	v_exp_f32_e32 v59, v59
	v_pk_fma_f32 v[62:63], v[62:63], s[22:23], v[76:77] op_sel_hi:[1,0,1] neg_lo:[1,0,0] neg_hi:[1,0,0]
	v_pk_fma_f32 v[64:65], v[64:65], s[22:23], v[72:73] op_sel_hi:[1,0,1] neg_lo:[1,0,0] neg_hi:[1,0,0]
	v_exp_f32_e32 v62, v62
	v_pk_add_f32 v[58:59], v[58:59], 1.0 op_sel_hi:[1,0]
	v_exp_f32_e32 v63, v63
	v_rcp_f32_e32 v58, v58
	v_rcp_f32_e32 v59, v59
	v_exp_f32_e32 v64, v64
	v_exp_f32_e32 v65, v65
	v_pk_fma_f32 v[50:51], v[50:51], s[22:23], v[70:71] op_sel_hi:[1,0,1] neg_lo:[1,0,0] neg_hi:[1,0,0]
	v_pk_mul_f32 v[78:79], v[148:149], v[58:59] op_sel_hi:[0,1]
	v_pk_fma_f32 v[58:59], v[60:61], s[22:23], v[68:69] op_sel_hi:[1,0,1] neg_lo:[1,0,0] neg_hi:[1,0,0]
	v_exp_f32_e32 v50, v50
	v_exp_f32_e32 v58, v58
	v_exp_f32_e32 v59, v59
	v_exp_f32_e32 v51, v51
	v_pk_add_f32 v[62:63], v[62:63], 1.0 op_sel_hi:[1,0]
	v_pk_add_f32 v[64:65], v[64:65], 1.0 op_sel_hi:[1,0]
	v_pk_add_f32 v[58:59], v[58:59], 1.0 op_sel_hi:[1,0]
	v_rcp_f32_e32 v62, v62
	v_rcp_f32_e32 v63, v63
	v_rcp_f32_e32 v64, v64
	v_rcp_f32_e32 v65, v65
	v_rcp_f32_e32 v58, v58
; #define GAS __attribute__((address_space(1)))
; __device__ __forceinline__ v4u pack8(const float (&f)[8]) { v4u w; w.x = pk2(f[0], f[1]); w.y = pk2(f[2], f[3]); w.z = pk2(f[4], f[5]); w.w = pk2(f[6], f[7]); return w; }
; __device__ __forceinline__ float fexp2(float x) { return __builtin_amdgcn_exp2f(x); }
; __device__ __forceinline__ float frcp(float x) { return __builtin_amdgcn_rcpf(x); }
;     __device__ __forceinline__ void operator()(const af4 (&acc)[2][2][4][2], const pg8::Unit& u, int wr, int wc, int fr, int fq) const {
;     ...
;             for (int ai = 0; ai < 2; ++ai)
; #pragma unroll
;                 for (int m = 0; m < 4; ++m) {
;                     const int row = row0 + ai * 128 + m * 16;
;                     float o[8];
; #pragma unroll
;                     for (int n = 0; n < 2; ++n)
; #pragma unroll
;                         for (int e = 0; e < 4; e += 2) {
;                             const f32x2 x = {acc[ai][bj][m][n][e], acc[ai][bj][m][n][e + 1]};
;                             const f32x2 ar = x * -1.4426950408889634f + (f32x2){bb[n][e], bb[n][e + 1]};
;                             const f32x2 den = (f32x2){fexp2(ar.x), fexp2(ar.y)} + 1.0f;
;                             const f32x2 r = (f32x2){frcp(den.x), frcp(den.y)} * sc;
;                             o[4 * n + e] = r.x; o[4 * n + e + 1] = r.y; }
;                     *(GAS v4u*)(EA + ((size_t)kind * MALL + row) * BW + c) = pack8(o);
	v_rcp_f32_e32 v59, v59
	v_pk_add_f32 v[50:51], v[50:51], 1.0 op_sel_hi:[1,0]
	v_pk_mul_f32 v[62:63], v[148:149], v[62:63] op_sel_hi:[0,1]
	v_rcp_f32_e32 v50, v50
	v_rcp_f32_e32 v51, v51
	v_pk_mul_f32 v[64:65], v[148:149], v[64:65] op_sel_hi:[0,1]
	v_pk_mul_f32 v[80:81], v[148:149], v[58:59] op_sel_hi:[0,1]
	v_cvt_pk_bf16_f32 v58, v62, v63
	v_cvt_pk_bf16_f32 v59, v64, v65
	v_cvt_pk_bf16_f32 v60, v78, v79
	v_cvt_pk_bf16_f32 v61, v80, v81
	global_store_dwordx4 v[122:123], v[58:61], off offset:256
	v_pk_fma_f32 v[54:55], v[54:55], s[22:23], v[76:77] op_sel_hi:[1,0,1] neg_lo:[1,0,0] neg_hi:[1,0,0]
	v_pk_fma_f32 v[56:57], v[56:57], s[22:23], v[72:73] op_sel_hi:[1,0,1] neg_lo:[1,0,0] neg_hi:[1,0,0]
	v_pk_mul_f32 v[58:59], v[148:149], v[50:51] op_sel_hi:[0,1]
	v_pk_fma_f32 v[50:51], v[52:53], s[22:23], v[68:69] op_sel_hi:[1,0,1] neg_lo:[1,0,0] neg_hi:[1,0,0]
	v_exp_f32_e32 v54, v54
	v_exp_f32_e32 v55, v55
	v_exp_f32_e32 v56, v56
	v_exp_f32_e32 v57, v57
	v_exp_f32_e32 v50, v50
	v_exp_f32_e32 v51, v51
	v_pk_fma_f32 v[42:43], v[42:43], s[22:23], v[70:71] op_sel_hi:[1,0,1] neg_lo:[1,0,0] neg_hi:[1,0,0]
	v_pk_add_f32 v[54:55], v[54:55], 1.0 op_sel_hi:[1,0]
	v_exp_f32_e32 v42, v42
	v_exp_f32_e32 v43, v43
	v_pk_add_f32 v[56:57], v[56:57], 1.0 op_sel_hi:[1,0]
	v_pk_add_f32 v[50:51], v[50:51], 1.0 op_sel_hi:[1,0]
	v_rcp_f32_e32 v54, v54
	v_rcp_f32_e32 v55, v55
	v_rcp_f32_e32 v56, v56
	v_rcp_f32_e32 v57, v57
	v_rcp_f32_e32 v50, v50
	v_rcp_f32_e32 v51, v51
	v_pk_add_f32 v[42:43], v[42:43], 1.0 op_sel_hi:[1,0]
	v_pk_mul_f32 v[54:55], v[148:149], v[54:55] op_sel_hi:[0,1]
	v_rcp_f32_e32 v42, v42
	v_rcp_f32_e32 v43, v43
	v_pk_mul_f32 v[56:57], v[148:149], v[56:57] op_sel_hi:[0,1]
	v_pk_mul_f32 v[60:61], v[148:149], v[50:51] op_sel_hi:[0,1]
	v_cvt_pk_bf16_f32 v50, v54, v55
	v_cvt_pk_bf16_f32 v51, v56, v57
	v_cvt_pk_bf16_f32 v52, v58, v59
	v_cvt_pk_bf16_f32 v53, v60, v61
	global_store_dwordx4 v[114:115], v[50:53], off offset:256
	v_pk_fma_f32 v[46:47], v[46:47], s[22:23], v[76:77] op_sel_hi:[1,0,1] neg_lo:[1,0,0] neg_hi:[1,0,0]
	v_pk_fma_f32 v[48:49], v[48:49], s[22:23], v[72:73] op_sel_hi:[1,0,1] neg_lo:[1,0,0] neg_hi:[1,0,0]
	v_pk_mul_f32 v[50:51], v[148:149], v[42:43] op_sel_hi:[0,1]
	v_pk_fma_f32 v[42:43], v[44:45], s[22:23], v[68:69] op_sel_hi:[1,0,1] neg_lo:[1,0,0] neg_hi:[1,0,0]
	v_exp_f32_e32 v46, v46
	v_exp_f32_e32 v47, v47
	v_exp_f32_e32 v48, v48
	v_exp_f32_e32 v49, v49
	v_exp_f32_e32 v42, v42
	v_exp_f32_e32 v43, v43
	v_pk_fma_f32 v[34:35], v[34:35], s[22:23], v[70:71] op_sel_hi:[1,0,1] neg_lo:[1,0,0] neg_hi:[1,0,0]
	v_pk_add_f32 v[46:47], v[46:47], 1.0 op_sel_hi:[1,0]
	v_exp_f32_e32 v34, v34
	v_exp_f32_e32 v35, v35
	v_pk_add_f32 v[48:49], v[48:49], 1.0 op_sel_hi:[1,0]
	v_pk_add_f32 v[42:43], v[42:43], 1.0 op_sel_hi:[1,0]
	v_rcp_f32_e32 v46, v46
	v_rcp_f32_e32 v47, v47
	v_rcp_f32_e32 v48, v48
	v_rcp_f32_e32 v49, v49
	v_rcp_f32_e32 v42, v42
	v_rcp_f32_e32 v43, v43
	v_pk_add_f32 v[34:35], v[34:35], 1.0 op_sel_hi:[1,0]
	v_pk_mul_f32 v[46:47], v[148:149], v[46:47] op_sel_hi:[0,1]
	v_rcp_f32_e32 v34, v34
	v_rcp_f32_e32 v35, v35
	v_pk_mul_f32 v[48:49], v[148:149], v[48:49] op_sel_hi:[0,1]
	v_pk_mul_f32 v[52:53], v[148:149], v[42:43] op_sel_hi:[0,1]
	v_cvt_pk_bf16_f32 v42, v46, v47
	v_cvt_pk_bf16_f32 v43, v48, v49
	v_cvt_pk_bf16_f32 v44, v50, v51
	v_cvt_pk_bf16_f32 v45, v52, v53
	global_store_dwordx4 v[106:107], v[42:45], off offset:256
	v_pk_fma_f32 v[38:39], v[38:39], s[22:23], v[76:77] op_sel_hi:[1,0,1] neg_lo:[1,0,0] neg_hi:[1,0,0]
	v_pk_fma_f32 v[40:41], v[40:41], s[22:23], v[72:73] op_sel_hi:[1,0,1] neg_lo:[1,0,0] neg_hi:[1,0,0]
	v_pk_mul_f32 v[42:43], v[148:149], v[34:35] op_sel_hi:[0,1]
	v_pk_fma_f32 v[34:35], v[36:37], s[22:23], v[68:69] op_sel_hi:[1,0,1] neg_lo:[1,0,0] neg_hi:[1,0,0]
	v_exp_f32_e32 v38, v38
	v_exp_f32_e32 v39, v39
	v_exp_f32_e32 v40, v40
	v_exp_f32_e32 v41, v41
	v_exp_f32_e32 v34, v34
	v_exp_f32_e32 v35, v35
	v_pk_fma_f32 v[26:27], v[26:27], s[22:23], v[70:71] op_sel_hi:[1,0,1] neg_lo:[1,0,0] neg_hi:[1,0,0]
	v_pk_add_f32 v[38:39], v[38:39], 1.0 op_sel_hi:[1,0]
	v_exp_f32_e32 v26, v26
	v_exp_f32_e32 v27, v27
	v_pk_add_f32 v[40:41], v[40:41], 1.0 op_sel_hi:[1,0]
	v_pk_add_f32 v[34:35], v[34:35], 1.0 op_sel_hi:[1,0]
	v_rcp_f32_e32 v38, v38
	v_rcp_f32_e32 v39, v39
	v_rcp_f32_e32 v40, v40
	v_rcp_f32_e32 v41, v41
	v_rcp_f32_e32 v34, v34
	v_rcp_f32_e32 v35, v35
	v_pk_add_f32 v[26:27], v[26:27], 1.0 op_sel_hi:[1,0]
	v_pk_mul_f32 v[38:39], v[148:149], v[38:39] op_sel_hi:[0,1]
	v_rcp_f32_e32 v26, v26
	v_rcp_f32_e32 v27, v27
	v_pk_mul_f32 v[40:41], v[148:149], v[40:41] op_sel_hi:[0,1]
	v_pk_mul_f32 v[44:45], v[148:149], v[34:35] op_sel_hi:[0,1]
	v_cvt_pk_bf16_f32 v34, v38, v39
	v_cvt_pk_bf16_f32 v35, v40, v41
	v_cvt_pk_bf16_f32 v36, v42, v43
	v_cvt_pk_bf16_f32 v37, v44, v45
	global_store_dwordx4 v[98:99], v[34:37], off offset:256
	v_pk_fma_f32 v[30:31], v[30:31], s[22:23], v[76:77] op_sel_hi:[1,0,1] neg_lo:[1,0,0] neg_hi:[1,0,0]
	v_pk_fma_f32 v[32:33], v[32:33], s[22:23], v[72:73] op_sel_hi:[1,0,1] neg_lo:[1,0,0] neg_hi:[1,0,0]
	v_pk_mul_f32 v[34:35], v[148:149], v[26:27] op_sel_hi:[0,1]
	v_pk_fma_f32 v[26:27], v[28:29], s[22:23], v[68:69] op_sel_hi:[1,0,1] neg_lo:[1,0,0] neg_hi:[1,0,0]
; #define GAS __attribute__((address_space(1)))
; __device__ __forceinline__ v4u pack8(const float (&f)[8]) { v4u w; w.x = pk2(f[0], f[1]); w.y = pk2(f[2], f[3]); w.z = pk2(f[4], f[5]); w.w = pk2(f[6], f[7]); return w; }
; __device__ __forceinline__ float fexp2(float x) { return __builtin_amdgcn_exp2f(x); }
; __device__ __forceinline__ float frcp(float x) { return __builtin_amdgcn_rcpf(x); }
; template <class Epi, class Sched, bool ALIGN_EPI = false, bool SP2 = false>
; __device__ __forceinline__ void gemm_phase(PG8_LAS unsigned char* lds, const Gemm g, const Sched& S, const Epi& E) {
;     ...
;         if (!has_next) break;
;     __device__ __forceinline__ void operator()(const af4 (&acc)[2][2][4][2], const pg8::Unit& u, int wr, int wc, int fr, int fq) const {
;     ...
;             for (int ai = 0; ai < 2; ++ai)
; #pragma unroll
;                 for (int m = 0; m < 4; ++m) {
;                     const int row = row0 + ai * 128 + m * 16;
;                     float o[8];
; #pragma unroll
;                     for (int n = 0; n < 2; ++n)
; #pragma unroll
;                         for (int e = 0; e < 4; e += 2) {
;                             const f32x2 x = {acc[ai][bj][m][n][e], acc[ai][bj][m][n][e + 1]};
;                             const f32x2 ar = x * -1.4426950408889634f + (f32x2){bb[n][e], bb[n][e + 1]};
;                             const f32x2 den = (f32x2){fexp2(ar.x), fexp2(ar.y)} + 1.0f;
;                             const f32x2 r = (f32x2){frcp(den.x), frcp(den.y)} * sc;
;                             o[4 * n + e] = r.x; o[4 * n + e + 1] = r.y; }
;                     *(GAS v4u*)(EA + ((size_t)kind * MALL + row) * BW + c) = pack8(o);
	v_exp_f32_e32 v30, v30
	v_exp_f32_e32 v31, v31
	v_exp_f32_e32 v32, v32
	v_exp_f32_e32 v33, v33
	v_exp_f32_e32 v26, v26
	v_exp_f32_e32 v27, v27
	v_pk_fma_f32 v[18:19], v[18:19], s[22:23], v[70:71] op_sel_hi:[1,0,1] neg_lo:[1,0,0] neg_hi:[1,0,0]
	v_pk_add_f32 v[30:31], v[30:31], 1.0 op_sel_hi:[1,0]
	v_exp_f32_e32 v18, v18
	v_exp_f32_e32 v19, v19
	v_pk_add_f32 v[32:33], v[32:33], 1.0 op_sel_hi:[1,0]
	v_pk_add_f32 v[26:27], v[26:27], 1.0 op_sel_hi:[1,0]
	v_rcp_f32_e32 v30, v30
	v_rcp_f32_e32 v31, v31
	v_rcp_f32_e32 v32, v32
	v_rcp_f32_e32 v33, v33
	v_rcp_f32_e32 v26, v26
	v_rcp_f32_e32 v27, v27
	v_pk_add_f32 v[18:19], v[18:19], 1.0 op_sel_hi:[1,0]
	v_pk_mul_f32 v[30:31], v[148:149], v[30:31] op_sel_hi:[0,1]
	v_rcp_f32_e32 v18, v18
	v_rcp_f32_e32 v19, v19
	v_pk_mul_f32 v[32:33], v[148:149], v[32:33] op_sel_hi:[0,1]
	v_pk_mul_f32 v[36:37], v[148:149], v[26:27] op_sel_hi:[0,1]
	v_cvt_pk_bf16_f32 v26, v30, v31
	v_cvt_pk_bf16_f32 v27, v32, v33
	v_cvt_pk_bf16_f32 v28, v34, v35
	v_cvt_pk_bf16_f32 v29, v36, v37
	global_store_dwordx4 v[90:91], v[26:29], off offset:256
	v_pk_fma_f32 v[22:23], v[22:23], s[22:23], v[76:77] op_sel_hi:[1,0,1] neg_lo:[1,0,0] neg_hi:[1,0,0]
	v_pk_fma_f32 v[24:25], v[24:25], s[22:23], v[72:73] op_sel_hi:[1,0,1] neg_lo:[1,0,0] neg_hi:[1,0,0]
	v_pk_mul_f32 v[26:27], v[148:149], v[18:19] op_sel_hi:[0,1]
	v_pk_fma_f32 v[18:19], v[20:21], s[22:23], v[68:69] op_sel_hi:[1,0,1] neg_lo:[1,0,0] neg_hi:[1,0,0]
	v_exp_f32_e32 v22, v22
	v_exp_f32_e32 v23, v23
	v_exp_f32_e32 v24, v24
	v_exp_f32_e32 v25, v25
	v_exp_f32_e32 v18, v18
	v_exp_f32_e32 v19, v19
	v_pk_fma_f32 v[10:11], v[10:11], s[22:23], v[70:71] op_sel_hi:[1,0,1] neg_lo:[1,0,0] neg_hi:[1,0,0]
	v_pk_add_f32 v[22:23], v[22:23], 1.0 op_sel_hi:[1,0]
	v_exp_f32_e32 v10, v10
	v_exp_f32_e32 v11, v11
	v_pk_add_f32 v[24:25], v[24:25], 1.0 op_sel_hi:[1,0]
	v_pk_add_f32 v[18:19], v[18:19], 1.0 op_sel_hi:[1,0]
	v_rcp_f32_e32 v22, v22
	v_rcp_f32_e32 v23, v23
	v_rcp_f32_e32 v24, v24
	v_rcp_f32_e32 v25, v25
	v_rcp_f32_e32 v18, v18
	v_rcp_f32_e32 v19, v19
	v_pk_add_f32 v[10:11], v[10:11], 1.0 op_sel_hi:[1,0]
	v_pk_mul_f32 v[22:23], v[148:149], v[22:23] op_sel_hi:[0,1]
	v_rcp_f32_e32 v10, v10
	v_rcp_f32_e32 v11, v11
	v_pk_mul_f32 v[24:25], v[148:149], v[24:25] op_sel_hi:[0,1]
	v_pk_mul_f32 v[28:29], v[148:149], v[18:19] op_sel_hi:[0,1]
	v_cvt_pk_bf16_f32 v18, v22, v23
	v_cvt_pk_bf16_f32 v19, v24, v25
	v_cvt_pk_bf16_f32 v20, v26, v27
	v_cvt_pk_bf16_f32 v21, v28, v29
	global_store_dwordx4 v[82:83], v[18:21], off offset:256
	v_pk_fma_f32 v[14:15], v[14:15], s[22:23], v[76:77] op_sel_hi:[1,0,1] neg_lo:[1,0,0] neg_hi:[1,0,0]
	v_pk_fma_f32 v[16:17], v[16:17], s[22:23], v[72:73] op_sel_hi:[1,0,1] neg_lo:[1,0,0] neg_hi:[1,0,0]
	v_pk_mul_f32 v[18:19], v[148:149], v[10:11] op_sel_hi:[0,1]
	v_pk_fma_f32 v[10:11], v[12:13], s[22:23], v[68:69] op_sel_hi:[1,0,1] neg_lo:[1,0,0] neg_hi:[1,0,0]
	v_exp_f32_e32 v14, v14
	v_exp_f32_e32 v15, v15
	v_exp_f32_e32 v16, v16
	v_exp_f32_e32 v17, v17
	v_exp_f32_e32 v10, v10
	v_exp_f32_e32 v11, v11
	v_pk_fma_f32 v[2:3], v[2:3], s[22:23], v[70:71] op_sel_hi:[1,0,1] neg_lo:[1,0,0] neg_hi:[1,0,0]
	v_pk_add_f32 v[14:15], v[14:15], 1.0 op_sel_hi:[1,0]
	v_exp_f32_e32 v2, v2
	v_exp_f32_e32 v3, v3
	v_pk_add_f32 v[16:17], v[16:17], 1.0 op_sel_hi:[1,0]
	v_pk_add_f32 v[10:11], v[10:11], 1.0 op_sel_hi:[1,0]
	v_rcp_f32_e32 v14, v14
	v_rcp_f32_e32 v15, v15
	v_rcp_f32_e32 v16, v16
	v_rcp_f32_e32 v17, v17
	v_rcp_f32_e32 v10, v10
	v_rcp_f32_e32 v11, v11
	v_pk_add_f32 v[2:3], v[2:3], 1.0 op_sel_hi:[1,0]
	v_pk_mul_f32 v[14:15], v[148:149], v[14:15] op_sel_hi:[0,1]
	v_rcp_f32_e32 v2, v2
	v_rcp_f32_e32 v3, v3
	v_pk_mul_f32 v[16:17], v[148:149], v[16:17] op_sel_hi:[0,1]
	v_pk_mul_f32 v[20:21], v[148:149], v[10:11] op_sel_hi:[0,1]
	v_cvt_pk_bf16_f32 v10, v14, v15
	v_cvt_pk_bf16_f32 v11, v16, v17
	v_cvt_pk_bf16_f32 v12, v18, v19
	v_cvt_pk_bf16_f32 v13, v20, v21
	global_store_dwordx4 v[74:75], v[10:13], off offset:256
	v_pk_fma_f32 v[6:7], v[6:7], s[22:23], v[76:77] op_sel_hi:[1,0,1] neg_lo:[1,0,0] neg_hi:[1,0,0]
	v_pk_fma_f32 v[8:9], v[8:9], s[22:23], v[72:73] op_sel_hi:[1,0,1] neg_lo:[1,0,0] neg_hi:[1,0,0]
	v_pk_mul_f32 v[10:11], v[148:149], v[2:3] op_sel_hi:[0,1]
	v_pk_fma_f32 v[2:3], v[4:5], s[22:23], v[68:69] op_sel_hi:[1,0,1] neg_lo:[1,0,0] neg_hi:[1,0,0]
	v_exp_f32_e32 v6, v6
	v_exp_f32_e32 v7, v7
	v_exp_f32_e32 v8, v8
	v_exp_f32_e32 v9, v9
	v_exp_f32_e32 v2, v2
	v_exp_f32_e32 v3, v3
	v_pk_add_f32 v[6:7], v[6:7], 1.0 op_sel_hi:[1,0]
	v_pk_add_f32 v[8:9], v[8:9], 1.0 op_sel_hi:[1,0]
	v_rcp_f32_e32 v6, v6
	v_pk_add_f32 v[2:3], v[2:3], 1.0 op_sel_hi:[1,0]
	v_rcp_f32_e32 v7, v7
	v_rcp_f32_e32 v8, v8
	v_rcp_f32_e32 v9, v9
	v_rcp_f32_e32 v2, v2
	v_rcp_f32_e32 v3, v3
	v_pk_mul_f32 v[6:7], v[148:149], v[6:7] op_sel_hi:[0,1]
	v_pk_mul_f32 v[8:9], v[148:149], v[8:9] op_sel_hi:[0,1]
	v_pk_mul_f32 v[12:13], v[148:149], v[2:3] op_sel_hi:[0,1]
	v_cvt_pk_bf16_f32 v2, v6, v7
	v_cvt_pk_bf16_f32 v3, v8, v9
	v_cvt_pk_bf16_f32 v4, v10, v11
	v_cvt_pk_bf16_f32 v5, v12, v13
	global_store_dwordx4 v[66:67], v[2:5], off offset:256
	s_cbranch_vccnz .LBB0_515
	s_andn2_b64 vcc, exec, s[12:13]
	s_cbranch_vccnz .LBB0_514
	s_barrier
	s_branch .LBB0_514
